# MoBA next-unit atomic waited at unit end; prologue x-row loop waits no longer force the previous row's store acks
# speedup vs baseline: 1.0127x; 1.0041x over previous
; DI unsigned cvtpk(float lo, float hi) { typedef float f2 __attribute__((ext_vector_type(2))); typedef __bf16 b2 __attribute__((ext_vector_type(2))); f2 v = {lo, hi}; b2 b = __builtin_convertvector(v, b2); return __builtin_bit_cast(unsigned, b); }
; __global__ void __launch_bounds__(512, 2) hybrid_fwd(Params p) {
;     ...
;             while (row < T) {
;                 const int rn_ = row + NGW; const bool hn = rn_ < T;
;                 if (hn) {
; #pragma unroll
;                     for (int j = 0; j < 4; ++j) vb[j] = ((const f32x4*)(p.x + (size_t)rn_ * DM) + lane)[64 * j];
;                 }
;                 { float s = 0.f;
; #pragma unroll
;                   for (int j = 0; j < 4; ++j) s += (va[j].x * va[j].x + va[j].y * va[j].y) + (va[j].z * va[j].z + va[j].w * va[j].w);
;                   s = wave_sum(s);
;                   const float rn = 1.0f / sqrtf(s * (1.0f / DM) + RMS_EPS);
;                   u32x2* o8 = (u32x2*)(act + (size_t)row * PITCH + XB_COL) + lane;
; #pragma unroll
;                   for (int j = 0; j < 4; ++j) { u32x2 w; w.x = cvtpk(va[j].x * rn, va[j].y * rn); w.y = cvtpk(va[j].z * rn, va[j].w * rn); o8[64 * j] = w; }
;                   if (lane < 16) ssq[(size_t)row * 16 + lane] = (lane == 0) ? s : 0.f; }
;                 if (!hn) break;
;                 const int rn2_ = rn_ + NGW; const bool hn2 = rn2_ < T;
;                 if (hn2) {
; #pragma unroll
;                     for (int j = 0; j < 4; ++j) va[j] = ((const f32x4*)(p.x + (size_t)rn2_ * DM) + lane)[64 * j];
;                 }
.LBB0_119:
	s_cmpk_gt_i32 s16, 0x7fff
	s_mov_b64 s[12:13], -1
	s_cbranch_scc1 .LBB0_118
	s_add_i32 s18, s16, s91
	s_cmp_lt_i32 s18, 0x8000
	s_cselect_b64 s[20:21], -1, 0
	s_cmpk_gt_i32 s18, 0x7fff
	s_cbranch_scc1 .LBB0_122
	s_ashr_i32 s19, s18, 31
	s_lshl_b64 s[12:13], s[18:19], 12
	v_lshl_add_u64 v[40:41], v[34:35], 0, s[12:13]
	global_load_dwordx4 v[16:19], v[40:41], off nt
	global_load_dwordx4 v[20:23], v[40:41], off offset:1024 nt
	global_load_dwordx4 v[24:27], v[40:41], off offset:2048 nt
	global_load_dwordx4 v[28:31], v[40:41], off offset:3072 nt
	s_waitcnt vmcnt(9)
	s_branch .Lxa_join
.LBB0_122:
	s_waitcnt vmcnt(5)
.Lxa_join:
	v_pk_mul_f32 v[40:41], v[2:3], v[2:3]
	v_pk_mul_f32 v[42:43], v[0:1], v[0:1]
	v_mul_f32_e32 v32, v12, v12
	v_pk_mov_b32 v[44:45], v[42:43], v[40:41] op_sel:[1,0]
	v_mov_b32_e32 v43, v41
	v_pk_add_f32 v[40:41], v[44:45], v[42:43]
	v_pk_mul_f32 v[42:43], v[6:7], v[6:7]
	v_pk_mul_f32 v[44:45], v[4:5], v[4:5]
	v_pk_add_f32 v[40:41], v[40:41], v[40:41] op_sel:[0,1] op_sel_hi:[1,0]
	v_pk_mov_b32 v[46:47], v[44:45], v[42:43] op_sel:[1,0]
	v_mov_b32_e32 v45, v43
	v_pk_add_f32 v[42:43], v[46:47], v[44:45]
	v_mul_f32_e32 v44, v13, v13
	v_pk_add_f32 v[42:43], v[42:43], v[42:43] op_sel:[0,1] op_sel_hi:[1,0]
	v_mov_b32_e32 v41, v32
	v_mov_b32_e32 v43, v44
	v_mul_f32_e32 v32, v9, v9
	v_mul_f32_e32 v45, v14, v14
	v_pk_add_f32 v[40:41], v[40:41], v[42:43]
	v_pk_fma_f32 v[42:43], v[8:9], v[8:9], v[32:33] op_sel_hi:[1,1,0]
	v_mul_f32_e32 v32, v11, v11
	v_mul_f32_e32 v46, v15, v15
	v_mov_b32_e32 v43, v45
	v_pk_fma_f32 v[44:45], v[10:11], v[10:11], v[32:33] op_sel_hi:[1,1,0]
	s_nop 0
	v_mov_b32_e32 v45, v46
	v_pk_add_f32 v[42:43], v[42:43], v[44:45]
	s_nop 0
	v_pk_add_f32 v[40:41], v[40:41], v[42:43]
	s_nop 0
	v_add_f32_e32 v32, v40, v41
	v_and_b32_e32 v40, 64, v227
	v_add_u32_e32 v45, 64, v40
	v_xor_b32_e32 v40, 1, v227
	v_cmp_lt_i32_e32 vcc, v40, v45
	s_nop 1
	v_cndmask_b32_e32 v40, v227, v40, vcc
	v_lshlrev_b32_e32 v40, 2, v40
	ds_bpermute_b32 v41, v40, v32
	s_waitcnt lgkmcnt(0)
	v_add_f32_e32 v32, v32, v41
	v_xor_b32_e32 v41, 2, v227
	v_cmp_lt_i32_e32 vcc, v41, v45
	s_nop 1
	v_cndmask_b32_e32 v41, v227, v41, vcc
	v_lshlrev_b32_e32 v41, 2, v41
	ds_bpermute_b32 v42, v41, v32
	s_waitcnt lgkmcnt(0)
	v_add_f32_e32 v32, v32, v42
	v_xor_b32_e32 v42, 4, v227
	v_cmp_lt_i32_e32 vcc, v42, v45
	s_nop 1
	v_cndmask_b32_e32 v42, v227, v42, vcc
	v_lshlrev_b32_e32 v42, 2, v42
	ds_bpermute_b32 v43, v42, v32
	s_waitcnt lgkmcnt(0)
	v_add_f32_e32 v32, v32, v43
	v_xor_b32_e32 v43, 8, v227
	v_cmp_lt_i32_e32 vcc, v43, v45
	s_nop 1
	v_cndmask_b32_e32 v43, v227, v43, vcc
	v_lshlrev_b32_e32 v43, 2, v43
	ds_bpermute_b32 v44, v43, v32
	s_waitcnt lgkmcnt(0)
	v_add_f32_e32 v32, v32, v44
	v_xor_b32_e32 v44, 16, v227
	v_cmp_lt_i32_e32 vcc, v44, v45
	s_nop 1
	v_cndmask_b32_e32 v44, v227, v44, vcc
	v_lshlrev_b32_e32 v44, 2, v44
	ds_bpermute_b32 v46, v44, v32
	s_waitcnt lgkmcnt(0)
	v_add_f32_e32 v32, v32, v46
	v_xor_b32_e32 v46, 32, v227
	v_cmp_lt_i32_e32 vcc, v46, v45
	s_nop 1
	v_cndmask_b32_e32 v45, v227, v46, vcc
	v_lshlrev_b32_e32 v45, 2, v45
	ds_bpermute_b32 v46, v45, v32
	s_waitcnt lgkmcnt(0)
	v_add_f32_e32 v46, v32, v46
	v_fmamk_f32 v32, v46, 0x3a800000, v38
	v_mul_f32_e32 v47, 0x4f800000, v32
	v_cmp_gt_f32_e32 vcc, s25, v32
	s_nop 1
	v_cndmask_b32_e32 v32, v32, v47, vcc
	v_sqrt_f32_e32 v47, v32
	s_nop 0
	v_add_u32_e32 v48, -1, v47
	v_fma_f32 v49, -v48, v47, v32
	v_cmp_ge_f32_e64 s[12:13], 0, v49
	v_add_u32_e32 v49, 1, v47
	s_nop 0
	v_cndmask_b32_e64 v48, v47, v48, s[12:13]
	v_fma_f32 v47, -v49, v47, v32
	v_cmp_lt_f32_e64 s[12:13], 0, v47
	s_nop 1
	v_cndmask_b32_e64 v47, v48, v49, s[12:13]
	v_mul_f32_e32 v48, 0x37800000, v47
	v_cndmask_b32_e32 v47, v47, v48, vcc
	v_cmp_class_f32_e32 vcc, v32, v39
	s_nop 1
	v_cndmask_b32_e32 v32, v47, v32, vcc
	v_div_scale_f32 v47, s[12:13], v32, v32, 1.0
	v_rcp_f32_e32 v48, v47
	s_mul_i32 s12, s16, 0x3200
	s_mul_hi_i32 s13, s16, 0x3200
	s_add_u32 s12, s3, s12
	v_fma_f32 v49, -v47, v48, 1.0
	v_fmac_f32_e32 v48, v49, v48
	v_div_scale_f32 v49, vcc, 1.0, v32, 1.0
	v_mul_f32_e32 v50, v49, v48
	v_fma_f32 v51, -v47, v50, v49
	v_fmac_f32_e32 v50, v51, v48
	v_fma_f32 v47, -v47, v50, v49
	v_div_fmas_f32 v47, v47, v48, v50
	v_div_fixup_f32 v48, v47, v32, 1.0
	s_addc_u32 s13, s24, s13
	v_lshlrev_b32_e32 v32, 3, v72
	v_lshl_add_u64 v[50:51], s[12:13], 0, v[32:33]
	v_lshl_add_u64 v[52:53], v[50:51], 0, s[14:15]
	v_pk_mul_f32 v[54:55], v[48:49], v[0:1] op_sel_hi:[0,1]
	v_pk_mul_f32 v[56:57], v[48:49], v[2:3] op_sel_hi:[0,1]
	v_add_co_u32_e32 v50, vcc, s26, v50
	v_cvt_pk_bf16_f32 v54, v54, v55
	v_cvt_pk_bf16_f32 v55, v56, v57
	v_addc_co_u32_e32 v51, vcc, 0, v51, vcc
	global_store_dwordx2 v[50:51], v[54:55], off offset:2560
	v_pk_mul_f32 v[50:51], v[48:49], v[4:5] op_sel_hi:[0,1]
	v_pk_mul_f32 v[54:55], v[48:49], v[6:7] op_sel_hi:[0,1]
	v_cvt_pk_bf16_f32 v50, v50, v51
	v_cvt_pk_bf16_f32 v51, v54, v55
	global_store_dwordx2 v[52:53], v[50:51], off offset:512
	v_pk_mul_f32 v[50:51], v[48:49], v[8:9] op_sel_hi:[0,1]
	v_pk_mul_f32 v[54:55], v[48:49], v[10:11] op_sel_hi:[0,1]
	v_cvt_pk_bf16_f32 v50, v50, v51
	v_cvt_pk_bf16_f32 v51, v54, v55
	global_store_dwordx2 v[52:53], v[50:51], off offset:1024
	v_pk_mul_f32 v[50:51], v[48:49], v[12:13] op_sel_hi:[0,1]
	v_pk_mul_f32 v[48:49], v[48:49], v[14:15] op_sel_hi:[0,1]
	v_cvt_pk_bf16_f32 v50, v50, v51
	v_cvt_pk_bf16_f32 v51, v48, v49
	global_store_dwordx2 v[52:53], v[50:51], off offset:1536
	s_and_saveexec_b64 s[12:13], s[8:9]
	s_cbranch_execz .LBB0_124
	s_ashr_i32 s17, s16, 31
	s_lshl_b64 s[22:23], s[16:17], 6
	v_lshl_add_u64 v[48:49], v[36:37], 0, s[22:23]
	v_cndmask_b32_e64 v46, 0, v46, s[10:11]
	global_store_dword v[48:49], v46, off
.LBB0_124:
	s_or_b64 exec, exec, s[12:13]
	s_andn2_b64 vcc, exec, s[20:21]
	s_mov_b64 s[20:21], 0
	s_cbranch_vccnz .LBB0_117
	s_add_i32 s22, s18, s91
	s_cmp_lt_i32 s22, 0x8000
	s_cselect_b64 s[20:21], -1, 0
	s_cmpk_gt_i32 s22, 0x7fff
	s_cbranch_scc1 .LBB0_127
	s_ashr_i32 s23, s22, 31
	s_lshl_b64 s[12:13], s[22:23], 12
	v_lshl_add_u64 v[46:47], v[34:35], 0, s[12:13]
	global_load_dwordx4 v[0:3], v[46:47], off nt
	global_load_dwordx4 v[4:7], v[46:47], off offset:1024 nt
	global_load_dwordx4 v[8:11], v[46:47], off offset:2048 nt
	global_load_dwordx4 v[12:15], v[46:47], off offset:3072 nt
	s_waitcnt vmcnt(9)
	s_branch .Lxb_join

; DI unsigned cvtpk(float lo, float hi) { typedef float f2 __attribute__((ext_vector_type(2))); typedef __bf16 b2 __attribute__((ext_vector_type(2))); f2 v = {lo, hi}; b2 b = __builtin_convertvector(v, b2); return __builtin_bit_cast(unsigned, b); }
; __global__ void __launch_bounds__(512, 2) hybrid_fwd(Params p) {
;     ...
;                 { float s = 0.f;
; #pragma unroll
;                   for (int j = 0; j < 4; ++j) s += (vb[j].x * vb[j].x + vb[j].y * vb[j].y) + (vb[j].z * vb[j].z + vb[j].w * vb[j].w);
;                   s = wave_sum(s);
;                   const float rn = 1.0f / sqrtf(s * (1.0f / DM) + RMS_EPS);
;                   u32x2* o8 = (u32x2*)(act + (size_t)rn_ * PITCH + XB_COL) + lane;
; #pragma unroll
;                   for (int j = 0; j < 4; ++j) { u32x2 w; w.x = cvtpk(vb[j].x * rn, vb[j].y * rn); w.y = cvtpk(vb[j].z * rn, vb[j].w * rn); o8[64 * j] = w; }
;                   if (lane < 16) ssq[(size_t)rn_ * 16 + lane] = (lane == 0) ? s : 0.f; }
;                 if (!hn2) break;
;                 row = rn2_;
.Lxb_join:
	v_pk_mul_f32 v[46:47], v[18:19], v[18:19]
	v_pk_mul_f32 v[48:49], v[16:17], v[16:17]
	s_nop 0
	v_pk_mov_b32 v[50:51], v[48:49], v[46:47] op_sel:[1,0]
	v_mov_b32_e32 v49, v47
	v_pk_add_f32 v[46:47], v[50:51], v[48:49]
	v_pk_mul_f32 v[48:49], v[22:23], v[22:23]
	v_pk_mul_f32 v[50:51], v[20:21], v[20:21]
	v_pk_add_f32 v[46:47], v[46:47], v[46:47] op_sel:[0,1] op_sel_hi:[1,0]
	v_pk_mov_b32 v[52:53], v[50:51], v[48:49] op_sel:[1,0]
	v_mov_b32_e32 v51, v49
	v_pk_add_f32 v[48:49], v[52:53], v[50:51]
	v_mul_f32_e32 v50, v28, v28
	v_mul_f32_e32 v51, v29, v29
	v_pk_add_f32 v[48:49], v[48:49], v[48:49] op_sel:[0,1] op_sel_hi:[1,0]
	v_mov_b32_e32 v47, v50
	v_mov_b32_e32 v49, v51
	v_pk_add_f32 v[46:47], v[46:47], v[48:49]
	v_mul_f32_e32 v48, v25, v25
	v_mul_f32_e32 v50, v27, v27
	v_mul_f32_e32 v52, v30, v30
	v_mul_f32_e32 v53, v31, v31
	v_pk_fma_f32 v[48:49], v[24:25], v[24:25], v[48:49] op_sel_hi:[1,1,0]
	v_pk_fma_f32 v[50:51], v[26:27], v[26:27], v[50:51] op_sel_hi:[1,1,0]
	v_mov_b32_e32 v49, v52
	v_mov_b32_e32 v51, v53
	v_pk_add_f32 v[48:49], v[48:49], v[50:51]
	s_nop 0
	v_pk_add_f32 v[46:47], v[46:47], v[48:49]
	s_nop 0
	v_add_f32_e32 v46, v46, v47
	ds_bpermute_b32 v40, v40, v46
	s_waitcnt lgkmcnt(0)
	v_add_f32_e32 v40, v46, v40
	ds_bpermute_b32 v41, v41, v40
	s_waitcnt lgkmcnt(0)
	v_add_f32_e32 v40, v40, v41
	ds_bpermute_b32 v41, v42, v40
	s_waitcnt lgkmcnt(0)
	v_add_f32_e32 v40, v40, v41
	ds_bpermute_b32 v41, v43, v40
	s_waitcnt lgkmcnt(0)
	v_add_f32_e32 v40, v40, v41
	ds_bpermute_b32 v41, v44, v40
	s_waitcnt lgkmcnt(0)
	v_add_f32_e32 v40, v40, v41
	ds_bpermute_b32 v41, v45, v40
	s_waitcnt lgkmcnt(0)
	v_add_f32_e32 v40, v40, v41
	v_fmamk_f32 v41, v40, 0x3a800000, v38
	v_mul_f32_e32 v42, 0x4f800000, v41
	v_cmp_gt_f32_e32 vcc, s25, v41
	s_nop 1
	v_cndmask_b32_e32 v41, v41, v42, vcc
	v_sqrt_f32_e32 v42, v41
	s_nop 0
	v_add_u32_e32 v43, -1, v42
	v_add_u32_e32 v44, 1, v42
	v_fma_f32 v45, -v43, v42, v41
	v_fma_f32 v46, -v44, v42, v41
	v_cmp_ge_f32_e64 s[12:13], 0, v45
	s_nop 1
	v_cndmask_b32_e64 v42, v42, v43, s[12:13]
	v_cmp_lt_f32_e64 s[12:13], 0, v46
	s_nop 1
	v_cndmask_b32_e64 v42, v42, v44, s[12:13]
	v_mul_f32_e32 v43, 0x37800000, v42
	v_cndmask_b32_e32 v42, v42, v43, vcc
	v_cmp_class_f32_e32 vcc, v41, v39
	s_nop 1
	v_cndmask_b32_e32 v41, v42, v41, vcc
	v_div_scale_f32 v42, s[12:13], v41, v41, 1.0
	v_rcp_f32_e32 v43, v42
	v_div_scale_f32 v44, vcc, 1.0, v41, 1.0
	s_mul_i32 s12, s18, 0x3200
	v_fma_f32 v45, -v42, v43, 1.0
	v_fmac_f32_e32 v43, v45, v43
	v_mul_f32_e32 v45, v44, v43
	v_fma_f32 v46, -v42, v45, v44
	v_fmac_f32_e32 v45, v46, v43
	v_fma_f32 v42, -v42, v45, v44
	s_mul_hi_i32 s13, s18, 0x3200
	s_add_u32 s12, s3, s12
	v_div_fmas_f32 v42, v42, v43, v45
	s_addc_u32 s13, s24, s13
	v_div_fixup_f32 v42, v42, v41, 1.0
	v_lshl_add_u64 v[44:45], s[12:13], 0, v[32:33]
	v_lshl_add_u64 v[46:47], v[44:45], 0, s[14:15]
	v_pk_mul_f32 v[48:49], v[42:43], v[16:17] op_sel_hi:[0,1]
	v_pk_mul_f32 v[50:51], v[42:43], v[18:19] op_sel_hi:[0,1]
	v_add_co_u32_e32 v44, vcc, s26, v44
	v_cvt_pk_bf16_f32 v48, v48, v49
	v_cvt_pk_bf16_f32 v49, v50, v51
	v_addc_co_u32_e32 v45, vcc, 0, v45, vcc
	global_store_dwordx2 v[44:45], v[48:49], off offset:2560
	v_pk_mul_f32 v[44:45], v[42:43], v[20:21] op_sel_hi:[0,1]
	v_pk_mul_f32 v[48:49], v[42:43], v[22:23] op_sel_hi:[0,1]
	v_cvt_pk_bf16_f32 v44, v44, v45
	v_cvt_pk_bf16_f32 v45, v48, v49
	global_store_dwordx2 v[46:47], v[44:45], off offset:512
	v_pk_mul_f32 v[44:45], v[42:43], v[24:25] op_sel_hi:[0,1]
	v_pk_mul_f32 v[48:49], v[42:43], v[26:27] op_sel_hi:[0,1]
	v_cvt_pk_bf16_f32 v44, v44, v45
	v_cvt_pk_bf16_f32 v45, v48, v49
	global_store_dwordx2 v[46:47], v[44:45], off offset:1024
	v_pk_mul_f32 v[44:45], v[42:43], v[28:29] op_sel_hi:[0,1]
	v_pk_mul_f32 v[42:43], v[42:43], v[30:31] op_sel_hi:[0,1]
	v_cvt_pk_bf16_f32 v44, v44, v45
	v_cvt_pk_bf16_f32 v45, v42, v43
	global_store_dwordx2 v[46:47], v[44:45], off offset:1536
	s_and_saveexec_b64 s[12:13], s[8:9]
	s_cbranch_execz .LBB0_116
	s_ashr_i32 s19, s18, 31
	s_lshl_b64 s[18:19], s[18:19], 6
	v_lshl_add_u64 v[42:43], v[36:37], 0, s[18:19]
	v_cndmask_b32_e64 v32, 0, v40, s[10:11]
	global_store_dword v[42:43], v32, off
	s_branch .LBB0_116

; DI void moba_block_phase(bf16_t* act, const unsigned* sel, float* ml, unsigned* qctr, LAS const float* tabM, LAS unsigned char* lds, int tid, int wid, int lane) {
;     ...
;         int cnt = 0;
; #pragma unroll
;         for (int k = 0; k < 16; ++k) cnt += __popcll(__ballot(((words[k] >> j) & 1u) != 0u));
;         if (lane == 0) ctl[8 + wid] = (unsigned)cnt;
;         if (tid == 0) ctl[5] = 0u;
;         __syncthreads();
;         unsigned nxt_unit = 0u;
;         if (tid == 0) nxt_unit = __hip_atomic_fetch_add(qctr, 1u, __ATOMIC_RELAXED, __HIP_MEMORY_SCOPE_AGENT);
;         int off = 0, total = 0;
; #pragma unroll
;         for (int w = 0; w < 8; ++w) { const int c = (int)ctl[8 + w]; off += (w < wid) ? c : 0; total += c; }
; #pragma unroll
;         for (int k = 0; k < 16; ++k) {
;             const bool match = ((words[k] >> j) & 1u) != 0u;
;             const unsigned long long mask = __ballot(match);
;             if (match) list[off + __popcll(mask & ((1ull << lane) - 1ull))] = (unsigned short)((unsigned)(base + k * 64 + lane) | ((unsigned)__popc(words[k] & ((1u << j) - 1u)) << 13));
;             off += __popcll(mask);
;         }
.LBB0_441:
	s_or_b64 exec, exec, s[76:77]
	s_and_saveexec_b64 s[24:25], s[40:41]
	v_mov_b32_e32 v0, s88
	ds_write_b32 v0, v1
	s_or_b64 exec, exec, s[24:25]
	v_mov_b32_e32 v145, 0
	s_waitcnt lgkmcnt(0)
	s_barrier
	s_and_saveexec_b64 s[24:25], s[40:41]
	s_cbranch_execz .LBB0_447
	s_mov_b64 s[28:29], exec
	v_mbcnt_lo_u32_b32 v0, s28, 0
	v_mbcnt_hi_u32_b32 v0, s29, v0
	v_cmp_eq_u32_e64 s[76:77], 0, v0
	s_and_saveexec_b64 s[26:27], s[76:77]
	s_cbranch_execz .LBB0_446
	s_bcnt1_i32_b64 s28, s[28:29]
	v_mov_b32_e32 v245, s28
	v_readlane_b32 s28, v249, 10
	v_readlane_b32 s29, v249, 11
	s_nop 4
	global_atomic_add v245, v1, v245, s[28:29] sc0
.LBB0_446:
	s_or_b64 exec, exec, s[26:27]
.LBB0_447:
	s_or_b64 exec, exec, s[24:25]
	v_readlane_b32 s24, v250, 29
	v_add_u32_e32 v2, v144, v2
	v_add_u32_e32 v27, 0x100, v2
	v_mov_b32_e32 v0, s24
	ds_read_b32 v0, v0
	v_readlane_b32 s24, v250, 30
	v_lshlrev_b32_e64 v19, v19, -1
	v_cndmask_b32_e64 v28, 0, 1, s[74:75]
	v_mov_b32_e32 v2, s24
	ds_read_b32 v2, v2
	s_and_b64 s[24:25], s[6:7], exec
	s_waitcnt lgkmcnt(1)
	v_readfirstlane_b32 s24, v0
	s_cselect_b32 s26, s24, 0
	s_and_b64 s[24:25], s[8:9], exec
	s_waitcnt lgkmcnt(0)
	v_readfirstlane_b32 s24, v2
	v_readlane_b32 s25, v250, 31
	s_cselect_b32 s24, s24, 0
	s_add_i32 s26, s24, s26
	v_mov_b32_e32 v5, s25
	ds_read_b32 v5, v5
	s_and_b64 s[24:25], s[10:11], exec
	v_readlane_b32 s24, v250, 32
	v_lshlrev_b32_e32 v188, 6, v3
	v_add_u32_e32 v27, v27, v166
	v_mov_b32_e32 v22, s24
	ds_read_b32 v22, v22
	s_waitcnt lgkmcnt(1)
	v_readfirstlane_b32 s24, v5
	s_cselect_b32 s24, s24, 0
	s_add_i32 s26, s26, s24
	s_and_b64 s[24:25], s[12:13], exec
	s_waitcnt lgkmcnt(0)
	v_readfirstlane_b32 s24, v22
	v_readlane_b32 s25, v250, 33
	s_cselect_b32 s24, s24, 0
	s_add_i32 s26, s26, s24
	v_mov_b32_e32 v23, s25
	ds_read_b32 v23, v23
	s_and_b64 s[24:25], s[14:15], exec
	v_readlane_b32 s24, v250, 34
	v_not_b32_e32 v19, v19
	v_cmp_ne_u32_e64 s[76:77], 0, v28
	v_mov_b32_e32 v24, s24
	ds_read_b32 v24, v24
	s_waitcnt lgkmcnt(1)
	v_readfirstlane_b32 s24, v23
	s_cselect_b32 s24, s24, 0
	s_add_i32 s26, s26, s24
	s_and_b64 s[24:25], s[16:17], exec
	s_waitcnt lgkmcnt(0)
	v_readfirstlane_b32 s24, v24
	v_readlane_b32 s25, v250, 35
	s_cselect_b32 s24, s24, 0
	s_add_i32 s26, s26, s24
	v_mov_b32_e32 v25, s25
	ds_read_b32 v25, v25
	s_and_b64 s[24:25], s[18:19], exec
	v_readlane_b32 s24, v250, 36
	s_nop 1
	v_mov_b32_e32 v26, s24
	ds_read_b32 v26, v26
	s_waitcnt lgkmcnt(1)
	v_readfirstlane_b32 s24, v25
	s_cselect_b32 s24, s24, 0
	s_add_i32 s26, s26, s24
	s_and_b64 s[24:25], s[20:21], exec
	s_waitcnt lgkmcnt(0)
	v_readfirstlane_b32 s24, v26
	s_cselect_b32 s24, s24, 0
	s_add_i32 s26, s26, s24
	s_and_saveexec_b64 s[24:25], s[74:75]
	s_cbranch_execz .LBB0_449
	v_and_b32_e32 v29, s76, v134
	v_and_b32_e32 v28, s77, v135
	v_bcnt_u32_b32 v29, v29, 0
	s_lshl_b32 s27, s26, 1
	v_and_b32_e32 v21, v21, v19
	v_bcnt_u32_b32 v28, v28, v29
	s_add_i32 s27, s27, 0
	v_bcnt_u32_b32 v21, v21, 0
	v_lshl_add_u32 v28, v28, 1, s27
	v_lshl_or_b32 v21, v21, 13, v27
	v_add_u32_e32 v28, 0x10000, v28
	ds_write_b16 v28, v21

; DI void moba_block_phase(bf16_t* act, const unsigned* sel, float* ml, unsigned* qctr, LAS const float* tabM, LAS unsigned char* lds, int tid, int wid, int lane) {
;     ...
;         if (tid == 0) ctl[6] = nxt_unit;
.LBB0_530:
	s_and_saveexec_b64 s[24:25], s[40:41]
	s_cbranch_execz .LBB0_436
	v_readlane_b32 s26, v250, 28
	s_nop 1
	v_mov_b32_e32 v0, s26
	s_waitcnt vmcnt(0)
	ds_write_b32 v0, v245
	s_branch .LBB0_436
